# S0 adaLN GEMV loop also two batches in flight; on top of chain output-wave rewrite and modp fixes
# baseline (speedup 1.0000x reference)
; __device__ __forceinline__ void modp_task(const Params& p, int l, int task, LAS float* sl) {
;     ...
;     f32x4 acc[5];
; #pragma unroll
;     for (int r = 0; r < 5; ++r) acc[r] = (f32x4){0.f, 0.f, 0.f, 0.f};
;     const float* wp = p.w_ada + ((size_t)l * D + k0) * 12288 + n0;
; #pragma unroll 8
;     for (int kk = 0; kk < 64; ++kk) { const f32x4 w = __builtin_nontemporal_load((const f32x4*)(wp + (size_t)kk * 12288));
; #pragma unroll
;         for (int r = 0; r < 5; ++r) acc[r] += sl[r * 64 + kk] * w; }
; __global__ void __launch_bounds__(512, 2) mega(Params p_unused) {
;     ...
;       for (int it = bid; it < 192; it += G) modp_task(p, 0, it, ldsf);
.LBB0_9:
	s_or_b64 exec, exec, s[14:15]
	s_mul_i32 s14, s26, 6
	s_sub_i32 s14, s25, s14
	s_lshl_b32 s14, s14, 11
	s_mul_hi_i32 s15, s27, 0xc000
	s_mul_i32 s27, s27, 0xc000
	v_lshl_add_u32 v22, v1, 2, s14
	s_add_u32 s14, s6, s27
	s_addc_u32 s15, s7, s15
	v_ashrrev_i32_e32 v23, 31, v22
	v_mov_b32_e32 v2, 0
	v_lshl_add_u64 v[24:25], v[22:23], 2, s[14:15]
	s_mov_b64 s[14:15], 0
	s_mov_b32 s27, 0
	v_mov_b32_e32 v3, v2
	v_mov_b32_e32 v4, v2
	v_mov_b32_e32 v5, v2
	v_mov_b32_e32 v18, v2
	v_mov_b32_e32 v19, v2
	v_mov_b32_e32 v20, v2
	v_mov_b32_e32 v21, v2
	v_mov_b32_e32 v14, v2
	v_mov_b32_e32 v15, v2
	v_mov_b32_e32 v16, v2
	v_mov_b32_e32 v17, v2
	v_mov_b32_e32 v10, v2
	v_mov_b32_e32 v11, v2
	v_mov_b32_e32 v12, v2
	v_mov_b32_e32 v13, v2
	v_mov_b32_e32 v6, v2
	v_mov_b32_e32 v7, v2
	v_mov_b32_e32 v8, v2
	v_mov_b32_e32 v9, v2
	s_waitcnt lgkmcnt(0)
	s_barrier
	s_mov_b32 vcc_hi, 0
	v_lshl_add_u64 v[26:27], v[24:25], 0, s[14:15]
	v_mov_b64_e32 v[100:101], v[26:27]
	s_mov_b32 vcc_lo, 0x0
	v_lshl_add_u64 v[102:103], v[100:101], 0, vcc
	global_load_dwordx4 v[28:31], v[102:103], off nt
	s_mov_b32 vcc_lo, 0xc000
	v_lshl_add_u64 v[102:103], v[100:101], 0, vcc
	global_load_dwordx4 v[72:75], v[102:103], off nt
	s_mov_b32 vcc_lo, 0x18000
	v_lshl_add_u64 v[102:103], v[100:101], 0, vcc
	global_load_dwordx4 v[76:79], v[102:103], off nt
	s_mov_b32 vcc_lo, 0x24000
	v_lshl_add_u64 v[102:103], v[100:101], 0, vcc
	global_load_dwordx4 v[80:83], v[102:103], off nt
	s_mov_b32 vcc_lo, 0x30000
	v_lshl_add_u64 v[102:103], v[100:101], 0, vcc
	global_load_dwordx4 v[84:87], v[102:103], off nt
	s_mov_b32 vcc_lo, 0x3c000
	v_lshl_add_u64 v[102:103], v[100:101], 0, vcc
	global_load_dwordx4 v[88:91], v[102:103], off nt
	s_mov_b32 vcc_lo, 0x48000
	v_lshl_add_u64 v[102:103], v[100:101], 0, vcc
	global_load_dwordx4 v[92:95], v[102:103], off nt
	s_mov_b32 vcc_lo, 0x54000
	v_lshl_add_u64 v[102:103], v[100:101], 0, vcc
	global_load_dwordx4 v[96:99], v[102:103], off nt
.LBB0_10:
	v_lshl_add_u64 v[26:27], v[24:25], 0, s[14:15]
	s_mov_b32 vcc_lo, 0x60000
	v_lshl_add_u64 v[100:101], v[26:27], 0, vcc
	s_mov_b32 vcc_lo, 0x0
	v_lshl_add_u64 v[102:103], v[100:101], 0, vcc
	global_load_dwordx4 v[130:133], v[102:103], off nt
	s_mov_b32 vcc_lo, 0xc000
	v_lshl_add_u64 v[102:103], v[100:101], 0, vcc
	global_load_dwordx4 v[134:137], v[102:103], off nt
	s_mov_b32 vcc_lo, 0x18000
	v_lshl_add_u64 v[102:103], v[100:101], 0, vcc
	global_load_dwordx4 v[138:141], v[102:103], off nt
	s_mov_b32 vcc_lo, 0x24000
	v_lshl_add_u64 v[102:103], v[100:101], 0, vcc
	global_load_dwordx4 v[142:145], v[102:103], off nt
	s_mov_b32 vcc_lo, 0x30000
	v_lshl_add_u64 v[102:103], v[100:101], 0, vcc
	global_load_dwordx4 v[146:149], v[102:103], off nt
	s_mov_b32 vcc_lo, 0x3c000
	v_lshl_add_u64 v[102:103], v[100:101], 0, vcc
	global_load_dwordx4 v[150:153], v[102:103], off nt
	s_mov_b32 vcc_lo, 0x48000
	v_lshl_add_u64 v[102:103], v[100:101], 0, vcc
	global_load_dwordx4 v[154:157], v[102:103], off nt
	s_mov_b32 vcc_lo, 0x54000
	v_lshl_add_u64 v[102:103], v[100:101], 0, vcc
	global_load_dwordx4 v[158:161], v[102:103], off nt
	v_mov_b32_e32 v1, s27
	ds_read_b128 v[32:35], v1
	ds_read_b128 v[36:39], v1 offset:16
	ds_read_b128 v[40:43], v1 offset:256
	ds_read_b128 v[44:47], v1 offset:272
	ds_read_b128 v[48:51], v1 offset:512
	ds_read_b128 v[52:55], v1 offset:528
	ds_read_b128 v[56:59], v1 offset:768
	ds_read_b128 v[60:63], v1 offset:784
	ds_read_b128 v[64:67], v1 offset:1024
	ds_read_b128 v[68:71], v1 offset:1040
	s_waitcnt lgkmcnt(0)
	s_waitcnt vmcnt(15)
	v_fmac_f32_e32 v18, v32, v28
	v_fmac_f32_e32 v19, v32, v29
	v_fmac_f32_e32 v20, v32, v30
	v_fmac_f32_e32 v21, v32, v31
	v_fmac_f32_e32 v14, v40, v28
	v_fmac_f32_e32 v15, v40, v29
	v_fmac_f32_e32 v16, v40, v30
	v_fmac_f32_e32 v17, v40, v31
	v_fmac_f32_e32 v10, v48, v28
	v_fmac_f32_e32 v11, v48, v29
	v_fmac_f32_e32 v12, v48, v30
	v_fmac_f32_e32 v13, v48, v31
	v_fmac_f32_e32 v6, v56, v28
	v_fmac_f32_e32 v7, v56, v29
	v_fmac_f32_e32 v8, v56, v30
	v_fmac_f32_e32 v9, v56, v31
	v_fmac_f32_e32 v2, v64, v28
	v_fmac_f32_e32 v3, v64, v29
	v_fmac_f32_e32 v4, v64, v30
	v_fmac_f32_e32 v5, v64, v31
	s_waitcnt vmcnt(14)
	v_fmac_f32_e32 v18, v33, v72
	v_fmac_f32_e32 v19, v33, v73
	v_fmac_f32_e32 v20, v33, v74
	v_fmac_f32_e32 v21, v33, v75
	v_fmac_f32_e32 v14, v41, v72
	v_fmac_f32_e32 v15, v41, v73
	v_fmac_f32_e32 v16, v41, v74
	v_fmac_f32_e32 v17, v41, v75
	v_fmac_f32_e32 v10, v49, v72
	v_fmac_f32_e32 v11, v49, v73
	v_fmac_f32_e32 v12, v49, v74
	v_fmac_f32_e32 v13, v49, v75
	v_fmac_f32_e32 v6, v57, v72
	v_fmac_f32_e32 v7, v57, v73
	v_fmac_f32_e32 v8, v57, v74
	v_fmac_f32_e32 v9, v57, v75
	v_fmac_f32_e32 v2, v65, v72
	v_fmac_f32_e32 v3, v65, v73
	v_fmac_f32_e32 v4, v65, v74
	v_fmac_f32_e32 v5, v65, v75
	s_waitcnt vmcnt(13)
	v_fmac_f32_e32 v18, v34, v76
	v_fmac_f32_e32 v19, v34, v77
	v_fmac_f32_e32 v20, v34, v78
	v_fmac_f32_e32 v21, v34, v79
	v_fmac_f32_e32 v14, v42, v76
	v_fmac_f32_e32 v15, v42, v77
	v_fmac_f32_e32 v16, v42, v78
	v_fmac_f32_e32 v17, v42, v79
	v_fmac_f32_e32 v10, v50, v76
	v_fmac_f32_e32 v11, v50, v77
	v_fmac_f32_e32 v12, v50, v78
	v_fmac_f32_e32 v13, v50, v79
	v_fmac_f32_e32 v6, v58, v76
	v_fmac_f32_e32 v7, v58, v77
	v_fmac_f32_e32 v8, v58, v78
	v_fmac_f32_e32 v9, v58, v79
	v_fmac_f32_e32 v2, v66, v76
	v_fmac_f32_e32 v3, v66, v77
	v_fmac_f32_e32 v4, v66, v78
	v_fmac_f32_e32 v5, v66, v79
	s_waitcnt vmcnt(12)
; __device__ __forceinline__ void modp_task(const Params& p, int l, int task, LAS float* sl) {
;     ...
; #pragma unroll 8
;     for (int kk = 0; kk < 64; ++kk) { const f32x4 w = __builtin_nontemporal_load((const f32x4*)(wp + (size_t)kk * 12288));
; #pragma unroll
;         for (int r = 0; r < 5; ++r) acc[r] += sl[r * 64 + kk] * w; }
	v_fmac_f32_e32 v18, v35, v80
	v_fmac_f32_e32 v19, v35, v81
	v_fmac_f32_e32 v20, v35, v82
	v_fmac_f32_e32 v21, v35, v83
	v_fmac_f32_e32 v14, v43, v80
	v_fmac_f32_e32 v15, v43, v81
	v_fmac_f32_e32 v16, v43, v82
	v_fmac_f32_e32 v17, v43, v83
	v_fmac_f32_e32 v10, v51, v80
	v_fmac_f32_e32 v11, v51, v81
	v_fmac_f32_e32 v12, v51, v82
	v_fmac_f32_e32 v13, v51, v83
	v_fmac_f32_e32 v6, v59, v80
	v_fmac_f32_e32 v7, v59, v81
	v_fmac_f32_e32 v8, v59, v82
	v_fmac_f32_e32 v9, v59, v83
	v_fmac_f32_e32 v2, v67, v80
	v_fmac_f32_e32 v3, v67, v81
	v_fmac_f32_e32 v4, v67, v82
	v_fmac_f32_e32 v5, v67, v83
	s_waitcnt vmcnt(11)
	v_fmac_f32_e32 v18, v36, v84
	v_fmac_f32_e32 v19, v36, v85
	v_fmac_f32_e32 v20, v36, v86
	v_fmac_f32_e32 v21, v36, v87
	v_fmac_f32_e32 v14, v44, v84
	v_fmac_f32_e32 v15, v44, v85
	v_fmac_f32_e32 v16, v44, v86
	v_fmac_f32_e32 v17, v44, v87
	v_fmac_f32_e32 v10, v52, v84
	v_fmac_f32_e32 v11, v52, v85
	v_fmac_f32_e32 v12, v52, v86
	v_fmac_f32_e32 v13, v52, v87
	v_fmac_f32_e32 v6, v60, v84
	v_fmac_f32_e32 v7, v60, v85
	v_fmac_f32_e32 v8, v60, v86
	v_fmac_f32_e32 v9, v60, v87
	v_fmac_f32_e32 v2, v68, v84
	v_fmac_f32_e32 v3, v68, v85
	v_fmac_f32_e32 v4, v68, v86
	v_fmac_f32_e32 v5, v68, v87
	s_waitcnt vmcnt(10)
	v_fmac_f32_e32 v18, v37, v88
	v_fmac_f32_e32 v19, v37, v89
	v_fmac_f32_e32 v20, v37, v90
	v_fmac_f32_e32 v21, v37, v91
	v_fmac_f32_e32 v14, v45, v88
	v_fmac_f32_e32 v15, v45, v89
	v_fmac_f32_e32 v16, v45, v90
	v_fmac_f32_e32 v17, v45, v91
	v_fmac_f32_e32 v10, v53, v88
	v_fmac_f32_e32 v11, v53, v89
	v_fmac_f32_e32 v12, v53, v90
	v_fmac_f32_e32 v13, v53, v91
	v_fmac_f32_e32 v6, v61, v88
	v_fmac_f32_e32 v7, v61, v89
	v_fmac_f32_e32 v8, v61, v90
	v_fmac_f32_e32 v9, v61, v91
	v_fmac_f32_e32 v2, v69, v88
	v_fmac_f32_e32 v3, v69, v89
	v_fmac_f32_e32 v4, v69, v90
	v_fmac_f32_e32 v5, v69, v91
	s_waitcnt vmcnt(9)
	v_fmac_f32_e32 v18, v38, v92
	v_fmac_f32_e32 v19, v38, v93
	v_fmac_f32_e32 v20, v38, v94
	v_fmac_f32_e32 v21, v38, v95
	v_fmac_f32_e32 v14, v46, v92
	v_fmac_f32_e32 v15, v46, v93
	v_fmac_f32_e32 v16, v46, v94
	v_fmac_f32_e32 v17, v46, v95
	v_fmac_f32_e32 v10, v54, v92
	v_fmac_f32_e32 v11, v54, v93
	v_fmac_f32_e32 v12, v54, v94
	v_fmac_f32_e32 v13, v54, v95
	v_fmac_f32_e32 v6, v62, v92
	v_fmac_f32_e32 v7, v62, v93
	v_fmac_f32_e32 v8, v62, v94
	v_fmac_f32_e32 v9, v62, v95
	v_fmac_f32_e32 v2, v70, v92
	v_fmac_f32_e32 v3, v70, v93
	v_fmac_f32_e32 v4, v70, v94
	v_fmac_f32_e32 v5, v70, v95
	s_waitcnt vmcnt(8)
	v_fmac_f32_e32 v18, v39, v96
	v_fmac_f32_e32 v19, v39, v97
	v_fmac_f32_e32 v20, v39, v98
	v_fmac_f32_e32 v21, v39, v99
	v_fmac_f32_e32 v14, v47, v96
	v_fmac_f32_e32 v15, v47, v97
	v_fmac_f32_e32 v16, v47, v98
	v_fmac_f32_e32 v17, v47, v99
	v_fmac_f32_e32 v10, v55, v96
	v_fmac_f32_e32 v11, v55, v97
	v_fmac_f32_e32 v12, v55, v98
	v_fmac_f32_e32 v13, v55, v99
	v_fmac_f32_e32 v6, v63, v96
	v_fmac_f32_e32 v7, v63, v97
	v_fmac_f32_e32 v8, v63, v98
	v_fmac_f32_e32 v9, v63, v99
	v_fmac_f32_e32 v2, v71, v96
	v_fmac_f32_e32 v3, v71, v97
	v_fmac_f32_e32 v4, v71, v98
	v_fmac_f32_e32 v5, v71, v99
	s_add_u32 vcc_lo, s14, 0xc0000
	s_min_u32 vcc_lo, vcc_lo, 0x2a0000
	s_sub_u32 vcc_lo, vcc_lo, s14
	v_lshl_add_u64 v[100:101], v[26:27], 0, vcc
	s_mov_b32 vcc_lo, 0x0
	v_lshl_add_u64 v[102:103], v[100:101], 0, vcc
	global_load_dwordx4 v[28:31], v[102:103], off nt
	s_mov_b32 vcc_lo, 0xc000
	v_lshl_add_u64 v[102:103], v[100:101], 0, vcc
	global_load_dwordx4 v[72:75], v[102:103], off nt
	s_mov_b32 vcc_lo, 0x18000
	v_lshl_add_u64 v[102:103], v[100:101], 0, vcc
	global_load_dwordx4 v[76:79], v[102:103], off nt
	s_mov_b32 vcc_lo, 0x24000
	v_lshl_add_u64 v[102:103], v[100:101], 0, vcc
	global_load_dwordx4 v[80:83], v[102:103], off nt
	s_mov_b32 vcc_lo, 0x30000
	v_lshl_add_u64 v[102:103], v[100:101], 0, vcc
	global_load_dwordx4 v[84:87], v[102:103], off nt
	s_mov_b32 vcc_lo, 0x3c000
	v_lshl_add_u64 v[102:103], v[100:101], 0, vcc
	global_load_dwordx4 v[88:91], v[102:103], off nt
	s_mov_b32 vcc_lo, 0x48000
	v_lshl_add_u64 v[102:103], v[100:101], 0, vcc
	global_load_dwordx4 v[92:95], v[102:103], off nt
	s_mov_b32 vcc_lo, 0x54000
	v_lshl_add_u64 v[102:103], v[100:101], 0, vcc
	global_load_dwordx4 v[96:99], v[102:103], off nt
	s_add_i32 s27, s27, 32
	v_mov_b32_e32 v1, s27
	ds_read_b128 v[32:35], v1
	ds_read_b128 v[36:39], v1 offset:16
	ds_read_b128 v[40:43], v1 offset:256
	ds_read_b128 v[44:47], v1 offset:272
	ds_read_b128 v[48:51], v1 offset:512
	ds_read_b128 v[52:55], v1 offset:528
	ds_read_b128 v[56:59], v1 offset:768
	ds_read_b128 v[60:63], v1 offset:784
	ds_read_b128 v[64:67], v1 offset:1024
	ds_read_b128 v[68:71], v1 offset:1040
	s_waitcnt lgkmcnt(0)
	s_waitcnt vmcnt(15)
	v_fmac_f32_e32 v18, v32, v130
	v_fmac_f32_e32 v19, v32, v131
	v_fmac_f32_e32 v20, v32, v132
	v_fmac_f32_e32 v21, v32, v133
	v_fmac_f32_e32 v14, v40, v130
	v_fmac_f32_e32 v15, v40, v131
	v_fmac_f32_e32 v16, v40, v132
	v_fmac_f32_e32 v17, v40, v133
	v_fmac_f32_e32 v10, v48, v130
	v_fmac_f32_e32 v11, v48, v131
	v_fmac_f32_e32 v12, v48, v132
	v_fmac_f32_e32 v13, v48, v133
	v_fmac_f32_e32 v6, v56, v130
	v_fmac_f32_e32 v7, v56, v131
	v_fmac_f32_e32 v8, v56, v132
	v_fmac_f32_e32 v9, v56, v133
	v_fmac_f32_e32 v2, v64, v130
	v_fmac_f32_e32 v3, v64, v131
	v_fmac_f32_e32 v4, v64, v132
	v_fmac_f32_e32 v5, v64, v133
	s_waitcnt vmcnt(14)
; __device__ __forceinline__ void modp_task(const Params& p, int l, int task, LAS float* sl) {
;     ...
;     const float* wp = p.w_ada + ((size_t)l * D + k0) * 12288 + n0;
; #pragma unroll 8
;     for (int kk = 0; kk < 64; ++kk) { const f32x4 w = __builtin_nontemporal_load((const f32x4*)(wp + (size_t)kk * 12288));
; #pragma unroll
;         for (int r = 0; r < 5; ++r) acc[r] += sl[r * 64 + kk] * w; }
;     float* mp = (float*)(p.ws + OFF_MODP) + ((size_t)(s * 2 + l) * 5) * 12288 + n0;
; #pragma unroll
;     for (int r = 0; r < 5; ++r) *(f32x4*)(mp + (size_t)r * 12288) = acc[r];
; __global__ void __launch_bounds__(512, 2) mega(Params p_unused) {
;     ...
;       for (int it = bid; it < 192; it += G) modp_task(p, 0, it, ldsf);
	v_fmac_f32_e32 v18, v33, v134
	v_fmac_f32_e32 v19, v33, v135
	v_fmac_f32_e32 v20, v33, v136
	v_fmac_f32_e32 v21, v33, v137
	v_fmac_f32_e32 v14, v41, v134
	v_fmac_f32_e32 v15, v41, v135
	v_fmac_f32_e32 v16, v41, v136
	v_fmac_f32_e32 v17, v41, v137
	v_fmac_f32_e32 v10, v49, v134
	v_fmac_f32_e32 v11, v49, v135
	v_fmac_f32_e32 v12, v49, v136
	v_fmac_f32_e32 v13, v49, v137
	v_fmac_f32_e32 v6, v57, v134
	v_fmac_f32_e32 v7, v57, v135
	v_fmac_f32_e32 v8, v57, v136
	v_fmac_f32_e32 v9, v57, v137
	v_fmac_f32_e32 v2, v65, v134
	v_fmac_f32_e32 v3, v65, v135
	v_fmac_f32_e32 v4, v65, v136
	v_fmac_f32_e32 v5, v65, v137
	s_waitcnt vmcnt(13)
	v_fmac_f32_e32 v18, v34, v138
	v_fmac_f32_e32 v19, v34, v139
	v_fmac_f32_e32 v20, v34, v140
	v_fmac_f32_e32 v21, v34, v141
	v_fmac_f32_e32 v14, v42, v138
	v_fmac_f32_e32 v15, v42, v139
	v_fmac_f32_e32 v16, v42, v140
	v_fmac_f32_e32 v17, v42, v141
	v_fmac_f32_e32 v10, v50, v138
	v_fmac_f32_e32 v11, v50, v139
	v_fmac_f32_e32 v12, v50, v140
	v_fmac_f32_e32 v13, v50, v141
	v_fmac_f32_e32 v6, v58, v138
	v_fmac_f32_e32 v7, v58, v139
	v_fmac_f32_e32 v8, v58, v140
	v_fmac_f32_e32 v9, v58, v141
	v_fmac_f32_e32 v2, v66, v138
	v_fmac_f32_e32 v3, v66, v139
	v_fmac_f32_e32 v4, v66, v140
	v_fmac_f32_e32 v5, v66, v141
	s_waitcnt vmcnt(12)
	v_fmac_f32_e32 v18, v35, v142
	v_fmac_f32_e32 v19, v35, v143
	v_fmac_f32_e32 v20, v35, v144
	v_fmac_f32_e32 v21, v35, v145
	v_fmac_f32_e32 v14, v43, v142
	v_fmac_f32_e32 v15, v43, v143
	v_fmac_f32_e32 v16, v43, v144
	v_fmac_f32_e32 v17, v43, v145
	v_fmac_f32_e32 v10, v51, v142
	v_fmac_f32_e32 v11, v51, v143
	v_fmac_f32_e32 v12, v51, v144
	v_fmac_f32_e32 v13, v51, v145
	v_fmac_f32_e32 v6, v59, v142
	v_fmac_f32_e32 v7, v59, v143
	v_fmac_f32_e32 v8, v59, v144
	v_fmac_f32_e32 v9, v59, v145
	v_fmac_f32_e32 v2, v67, v142
	v_fmac_f32_e32 v3, v67, v143
	v_fmac_f32_e32 v4, v67, v144
	v_fmac_f32_e32 v5, v67, v145
	s_waitcnt vmcnt(11)
	v_fmac_f32_e32 v18, v36, v146
	v_fmac_f32_e32 v19, v36, v147
	v_fmac_f32_e32 v20, v36, v148
	v_fmac_f32_e32 v21, v36, v149
	v_fmac_f32_e32 v14, v44, v146
	v_fmac_f32_e32 v15, v44, v147
	v_fmac_f32_e32 v16, v44, v148
	v_fmac_f32_e32 v17, v44, v149
	v_fmac_f32_e32 v10, v52, v146
	v_fmac_f32_e32 v11, v52, v147
	v_fmac_f32_e32 v12, v52, v148
	v_fmac_f32_e32 v13, v52, v149
	v_fmac_f32_e32 v6, v60, v146
	v_fmac_f32_e32 v7, v60, v147
	v_fmac_f32_e32 v8, v60, v148
	v_fmac_f32_e32 v9, v60, v149
	v_fmac_f32_e32 v2, v68, v146
	v_fmac_f32_e32 v3, v68, v147
	v_fmac_f32_e32 v4, v68, v148
	v_fmac_f32_e32 v5, v68, v149
	s_waitcnt vmcnt(10)
	v_fmac_f32_e32 v18, v37, v150
	v_fmac_f32_e32 v19, v37, v151
	v_fmac_f32_e32 v20, v37, v152
	v_fmac_f32_e32 v21, v37, v153
	v_fmac_f32_e32 v14, v45, v150
	v_fmac_f32_e32 v15, v45, v151
	v_fmac_f32_e32 v16, v45, v152
	v_fmac_f32_e32 v17, v45, v153
	v_fmac_f32_e32 v10, v53, v150
	v_fmac_f32_e32 v11, v53, v151
	v_fmac_f32_e32 v12, v53, v152
	v_fmac_f32_e32 v13, v53, v153
	v_fmac_f32_e32 v6, v61, v150
	v_fmac_f32_e32 v7, v61, v151
	v_fmac_f32_e32 v8, v61, v152
	v_fmac_f32_e32 v9, v61, v153
	v_fmac_f32_e32 v2, v69, v150
	v_fmac_f32_e32 v3, v69, v151
	v_fmac_f32_e32 v4, v69, v152
	v_fmac_f32_e32 v5, v69, v153
	s_waitcnt vmcnt(9)
	v_fmac_f32_e32 v18, v38, v154
	v_fmac_f32_e32 v19, v38, v155
	v_fmac_f32_e32 v20, v38, v156
	v_fmac_f32_e32 v21, v38, v157
	v_fmac_f32_e32 v14, v46, v154
	v_fmac_f32_e32 v15, v46, v155
	v_fmac_f32_e32 v16, v46, v156
	v_fmac_f32_e32 v17, v46, v157
	v_fmac_f32_e32 v10, v54, v154
	v_fmac_f32_e32 v11, v54, v155
	v_fmac_f32_e32 v12, v54, v156
	v_fmac_f32_e32 v13, v54, v157
	v_fmac_f32_e32 v6, v62, v154
	v_fmac_f32_e32 v7, v62, v155
	v_fmac_f32_e32 v8, v62, v156
	v_fmac_f32_e32 v9, v62, v157
	v_fmac_f32_e32 v2, v70, v154
	v_fmac_f32_e32 v3, v70, v155
	v_fmac_f32_e32 v4, v70, v156
	v_fmac_f32_e32 v5, v70, v157
	s_waitcnt vmcnt(8)
	v_fmac_f32_e32 v18, v39, v158
	v_fmac_f32_e32 v19, v39, v159
	v_fmac_f32_e32 v20, v39, v160
	v_fmac_f32_e32 v21, v39, v161
	v_fmac_f32_e32 v14, v47, v158
	v_fmac_f32_e32 v15, v47, v159
	v_fmac_f32_e32 v16, v47, v160
	v_fmac_f32_e32 v17, v47, v161
	v_fmac_f32_e32 v10, v55, v158
	v_fmac_f32_e32 v11, v55, v159
	v_fmac_f32_e32 v12, v55, v160
	v_fmac_f32_e32 v13, v55, v161
	v_fmac_f32_e32 v6, v63, v158
	v_fmac_f32_e32 v7, v63, v159
	v_fmac_f32_e32 v8, v63, v160
	v_fmac_f32_e32 v9, v63, v161
	v_fmac_f32_e32 v2, v71, v158
	v_fmac_f32_e32 v3, v71, v159
	v_fmac_f32_e32 v4, v71, v160
	v_fmac_f32_e32 v5, v71, v161
	s_add_u32 s14, s14, 0xc0000
	s_addc_u32 s15, s15, 0
	s_add_i32 s27, s27, 32
	s_cmp_lg_u32 s14, 0x300000
	s_cbranch_scc1 .LBB0_10
	s_waitcnt vmcnt(0)
	s_lshl_b32 s14, s26, 1
	s_mul_i32 s26, s26, 0x78000
	s_mul_hi_i32 s15, s14, 0x3c000
	s_add_u32 s14, s1, s26
	s_addc_u32 s15, s16, s15
	v_lshl_add_u64 v[22:23], v[22:23], 2, s[14:15]
	global_store_dwordx4 v[22:23], v[18:21], off
	v_readlane_b32 s14, v239, 0
	s_add_i32 s25, s25, s14
	v_add_co_u32_e32 v18, vcc, s18, v22
	s_cmpk_gt_i32 s25, 0xbf
	s_nop 0
	v_addc_co_u32_e32 v19, vcc, 0, v23, vcc
	global_store_dwordx4 v[18:19], v[14:17], off
	v_readlane_b32 s15, v239, 1
	s_nop 0
	v_add_co_u32_e32 v14, vcc, s19, v22
	s_nop 1
	v_addc_co_u32_e32 v15, vcc, 0, v23, vcc
	global_store_dwordx4 v[14:15], v[10:13], off
	s_nop 1
	v_add_co_u32_e32 v10, vcc, 0x24000, v22
	s_nop 1
	v_addc_co_u32_e32 v11, vcc, 0, v23, vcc
	global_store_dwordx4 v[10:11], v[6:9], off
	s_nop 1
	v_add_co_u32_e32 v6, vcc, 0x30000, v22
	s_nop 1
	v_addc_co_u32_e32 v7, vcc, 0, v23, vcc
	global_store_dwordx4 v[6:7], v[2:5], off
	s_barrier
	s_cbranch_scc0 .LBB0_7
